# plus E3: T-row loads batched per trip in the small recurrence jobs and LDS reads issued ~10 ahead in the sequential chain step
# speedup vs baseline: 1.0240x; 1.0104x over previous
.LBB0_613:
	v_lshl_add_u64 v[18:19], v[8:9], 0, s[0:1]
	v_add_co_u32_e32 v22, vcc, 0xf948000, v18
	ds_read_b128 v[10:13], v7
	ds_read_b128 v[14:17], v7 offset:16
	v_addc_co_u32_e32 v23, vcc, 0, v19, vcc
	global_load_dwordx4 v[40:43], v[22:23], off
	global_load_dwordx4 v[44:47], v[22:23], off offset:256
	global_load_dwordx4 v[48:51], v[22:23], off offset:512
	global_load_dwordx4 v[52:55], v[22:23], off offset:768
	global_load_dwordx4 v[60:63], v[22:23], off offset:1024
	global_load_dwordx4 v[64:67], v[22:23], off offset:1280
	global_load_dwordx4 v[68:71], v[22:23], off offset:1536
	global_load_dwordx4 v[72:75], v[22:23], off offset:1792
	s_add_u32 s0, s0, 0x800
	s_addc_u32 s1, s1, 0
	v_add_u32_e32 v7, 32, v7
	s_waitcnt lgkmcnt(0)
	s_waitcnt vmcnt(7)
	v_pk_fma_f32 v[0:1], v[10:11], v[40:41], v[0:1] op_sel_hi:[0,1,1]
	v_pk_fma_f32 v[2:3], v[10:11], v[42:43], v[2:3] op_sel_hi:[0,1,1]
	s_waitcnt vmcnt(6)
	v_pk_fma_f32 v[0:1], v[10:11], v[44:45], v[0:1] op_sel:[1,0,0]
	v_pk_fma_f32 v[2:3], v[10:11], v[46:47], v[2:3] op_sel:[1,0,0]
	s_waitcnt vmcnt(5)
	v_pk_fma_f32 v[0:1], v[12:13], v[48:49], v[0:1] op_sel_hi:[0,1,1]
	v_pk_fma_f32 v[2:3], v[12:13], v[50:51], v[2:3] op_sel_hi:[0,1,1]
	s_waitcnt vmcnt(4)
	v_pk_fma_f32 v[0:1], v[12:13], v[52:53], v[0:1] op_sel:[1,0,0]
	v_pk_fma_f32 v[2:3], v[12:13], v[54:55], v[2:3] op_sel:[1,0,0]
	s_waitcnt vmcnt(3)
	v_pk_fma_f32 v[0:1], v[14:15], v[60:61], v[0:1] op_sel_hi:[0,1,1]
	v_pk_fma_f32 v[2:3], v[14:15], v[62:63], v[2:3] op_sel_hi:[0,1,1]
	s_waitcnt vmcnt(2)
	v_pk_fma_f32 v[0:1], v[14:15], v[64:65], v[0:1] op_sel:[1,0,0]
	v_pk_fma_f32 v[2:3], v[14:15], v[66:67], v[2:3] op_sel:[1,0,0]
	s_waitcnt vmcnt(1)
	v_pk_fma_f32 v[0:1], v[16:17], v[68:69], v[0:1] op_sel_hi:[0,1,1]
	v_pk_fma_f32 v[2:3], v[16:17], v[70:71], v[2:3] op_sel_hi:[0,1,1]
	s_waitcnt vmcnt(0)
	v_pk_fma_f32 v[0:1], v[16:17], v[72:73], v[0:1] op_sel:[1,0,0]
	v_pk_fma_f32 v[2:3], v[16:17], v[74:75], v[2:3] op_sel:[1,0,0]
	s_cmpk_eq_i32 s0, 0x4000
	s_cbranch_scc0 .LBB0_613
	s_add_i32 s5, s5, s40
	s_lshl_b32 s0, s5, 4
	s_lshl_b32 s1, s4, 3
	s_or_b32 s0, s0, s1
	s_or_b32 s0, s0, s3
	s_ashr_i32 s1, s0, 31
	s_lshl_b64 s[0:1], s[0:1], 14
	s_add_u32 s0, s36, s0
	s_addc_u32 s1, s37, s1
	v_lshl_add_u64 v[4:5], v[4:5], 2, s[0:1]
	v_lshlrev_b32_e32 v196, 2, v6
	s_add_i32 s2, s56, s2
	v_lshl_add_u64 v[4:5], v[4:5], 0, v[196:197]
	s_cmpk_gt_i32 s2, 0x7ff
	global_store_dwordx4 v[4:5], v[0:3], off
	s_cbranch_scc0 .LBB0_612

.LBB0_627:
	v_lshl_add_u64 v[16:17], v[6:7], 0, s[0:1]
	v_add_co_u32_e32 v20, vcc, 0xf948000, v16
	ds_read_b128 v[8:11], v34
	ds_read_b128 v[12:15], v34 offset:16
	v_addc_co_u32_e32 v21, vcc, 0, v17, vcc
	global_load_dwordx4 v[40:43], v[20:21], off
	global_load_dwordx4 v[44:47], v[20:21], off offset:256
	global_load_dwordx4 v[48:51], v[20:21], off offset:512
	global_load_dwordx4 v[52:55], v[20:21], off offset:768
	global_load_dwordx4 v[60:63], v[20:21], off offset:1024
	global_load_dwordx4 v[64:67], v[20:21], off offset:1280
	global_load_dwordx4 v[68:71], v[20:21], off offset:1536
	global_load_dwordx4 v[72:75], v[20:21], off offset:1792
	s_add_u32 s0, s0, 0x800
	s_addc_u32 s1, s1, 0
	v_add_u32_e32 v34, 32, v34
	s_waitcnt lgkmcnt(0)
	s_waitcnt vmcnt(7)
	v_pk_fma_f32 v[0:1], v[8:9], v[40:41], v[0:1] op_sel_hi:[0,1,1]
	v_pk_fma_f32 v[2:3], v[8:9], v[42:43], v[2:3] op_sel_hi:[0,1,1]
	s_waitcnt vmcnt(6)
	v_pk_fma_f32 v[0:1], v[8:9], v[44:45], v[0:1] op_sel:[1,0,0]
	v_pk_fma_f32 v[2:3], v[8:9], v[46:47], v[2:3] op_sel:[1,0,0]
	s_waitcnt vmcnt(5)
	v_pk_fma_f32 v[0:1], v[10:11], v[48:49], v[0:1] op_sel_hi:[0,1,1]
	v_pk_fma_f32 v[2:3], v[10:11], v[50:51], v[2:3] op_sel_hi:[0,1,1]
	s_waitcnt vmcnt(4)
	v_pk_fma_f32 v[0:1], v[10:11], v[52:53], v[0:1] op_sel:[1,0,0]
	v_pk_fma_f32 v[2:3], v[10:11], v[54:55], v[2:3] op_sel:[1,0,0]
	s_waitcnt vmcnt(3)
	v_pk_fma_f32 v[0:1], v[12:13], v[60:61], v[0:1] op_sel_hi:[0,1,1]
	v_pk_fma_f32 v[2:3], v[12:13], v[62:63], v[2:3] op_sel_hi:[0,1,1]
	s_waitcnt vmcnt(2)
	v_pk_fma_f32 v[0:1], v[12:13], v[64:65], v[0:1] op_sel:[1,0,0]
	v_pk_fma_f32 v[2:3], v[12:13], v[66:67], v[2:3] op_sel:[1,0,0]
	s_waitcnt vmcnt(1)
	v_pk_fma_f32 v[0:1], v[14:15], v[68:69], v[0:1] op_sel_hi:[0,1,1]
	v_pk_fma_f32 v[2:3], v[14:15], v[70:71], v[2:3] op_sel_hi:[0,1,1]
	s_waitcnt vmcnt(0)
	v_pk_fma_f32 v[0:1], v[14:15], v[72:73], v[0:1] op_sel:[1,0,0]
	v_pk_fma_f32 v[2:3], v[14:15], v[74:75], v[2:3] op_sel:[1,0,0]
	s_cmpk_eq_i32 s0, 0x4000
	s_cbranch_scc0 .LBB0_627
	v_lshl_add_u64 v[4:5], v[4:5], 2, s[24:25]
	v_lshl_add_u64 v[4:5], v[4:5], 0, v[196:197]
	global_store_dwordx4 v[4:5], v[0:3], off

.LBB0_678:
	ds_read_b128 v[48:51], v39
	ds_read_b128 v[80:83], v42
	ds_read_b128 v[84:87], v42 offset:256
	ds_read_b128 v[88:91], v42 offset:512
	ds_read_b128 v[92:95], v42 offset:768
	ds_read_b128 v[52:55], v39 offset:16
	ds_read_b128 v[96:99], v42 offset:1024
	ds_read_b128 v[100:103], v42 offset:1280
	ds_read_b128 v[104:107], v42 offset:1536
	ds_read_b128 v[108:111], v42 offset:1792
	ds_read_b128 v[56:59], v39 offset:32
	ds_read_b128 v[112:115], v42 offset:2048
	s_waitcnt lgkmcnt(10)
	v_pk_fma_f32 v[22:23], v[82:83], v[48:49], v[22:23] op_sel_hi:[1,0,1]
	v_pk_fma_f32 v[20:21], v[80:81], v[48:49], v[20:21] op_sel_hi:[1,0,1]
	ds_read_b128 v[116:119], v42 offset:2304
	s_waitcnt lgkmcnt(10)
	v_pk_fma_f32 v[22:23], v[86:87], v[48:49], v[22:23] op_sel:[0,1,0]
	v_pk_fma_f32 v[20:21], v[84:85], v[48:49], v[20:21] op_sel:[0,1,0]
	ds_read_b128 v[120:123], v42 offset:2560
	s_waitcnt lgkmcnt(10)
	v_pk_fma_f32 v[22:23], v[90:91], v[50:51], v[22:23] op_sel_hi:[1,0,1]
	v_pk_fma_f32 v[20:21], v[88:89], v[50:51], v[20:21] op_sel_hi:[1,0,1]
	ds_read_b128 v[124:127], v42 offset:2816
	s_waitcnt lgkmcnt(10)
	v_pk_fma_f32 v[22:23], v[94:95], v[50:51], v[22:23] op_sel:[0,1,0]
	v_pk_fma_f32 v[20:21], v[92:93], v[50:51], v[20:21] op_sel:[0,1,0]
	ds_read_b128 v[60:63], v39 offset:48
	ds_read_b128 v[80:83], v42 offset:3072
	s_waitcnt lgkmcnt(10)
	v_pk_fma_f32 v[22:23], v[98:99], v[52:53], v[22:23] op_sel_hi:[1,0,1]
	v_pk_fma_f32 v[20:21], v[96:97], v[52:53], v[20:21] op_sel_hi:[1,0,1]
	ds_read_b128 v[84:87], v42 offset:3328
	s_waitcnt lgkmcnt(10)
	v_pk_fma_f32 v[22:23], v[102:103], v[52:53], v[22:23] op_sel:[0,1,0]
	v_pk_fma_f32 v[20:21], v[100:101], v[52:53], v[20:21] op_sel:[0,1,0]
	ds_read_b128 v[88:91], v42 offset:3584
	s_waitcnt lgkmcnt(10)
	v_pk_fma_f32 v[22:23], v[106:107], v[54:55], v[22:23] op_sel_hi:[1,0,1]
	v_pk_fma_f32 v[20:21], v[104:105], v[54:55], v[20:21] op_sel_hi:[1,0,1]
	ds_read_b128 v[92:95], v42 offset:3840
	s_waitcnt lgkmcnt(10)
	v_pk_fma_f32 v[22:23], v[110:111], v[54:55], v[22:23] op_sel:[0,1,0]
	v_pk_fma_f32 v[20:21], v[108:109], v[54:55], v[20:21] op_sel:[0,1,0]
	ds_read_b128 v[48:51], v39 offset:64
	ds_read_b128 v[96:99], v42 offset:4096
	s_waitcnt lgkmcnt(10)
	v_pk_fma_f32 v[22:23], v[114:115], v[56:57], v[22:23] op_sel_hi:[1,0,1]
	v_pk_fma_f32 v[20:21], v[112:113], v[56:57], v[20:21] op_sel_hi:[1,0,1]
	ds_read_b128 v[100:103], v42 offset:4352
	s_waitcnt lgkmcnt(10)
	v_pk_fma_f32 v[22:23], v[118:119], v[56:57], v[22:23] op_sel:[0,1,0]
	v_pk_fma_f32 v[20:21], v[116:117], v[56:57], v[20:21] op_sel:[0,1,0]
	ds_read_b128 v[104:107], v42 offset:4608
	s_waitcnt lgkmcnt(10)
	v_pk_fma_f32 v[22:23], v[122:123], v[58:59], v[22:23] op_sel_hi:[1,0,1]
	v_pk_fma_f32 v[20:21], v[120:121], v[58:59], v[20:21] op_sel_hi:[1,0,1]
	ds_read_b128 v[108:111], v42 offset:4864
	s_waitcnt lgkmcnt(10)
	v_pk_fma_f32 v[22:23], v[126:127], v[58:59], v[22:23] op_sel:[0,1,0]
	v_pk_fma_f32 v[20:21], v[124:125], v[58:59], v[20:21] op_sel:[0,1,0]
	ds_read_b128 v[52:55], v39 offset:80
	ds_read_b128 v[112:115], v42 offset:5120
	s_waitcnt lgkmcnt(10)
	v_pk_fma_f32 v[22:23], v[82:83], v[60:61], v[22:23] op_sel_hi:[1,0,1]
	v_pk_fma_f32 v[20:21], v[80:81], v[60:61], v[20:21] op_sel_hi:[1,0,1]
	ds_read_b128 v[116:119], v42 offset:5376
	s_waitcnt lgkmcnt(10)
	v_pk_fma_f32 v[22:23], v[86:87], v[60:61], v[22:23] op_sel:[0,1,0]
	v_pk_fma_f32 v[20:21], v[84:85], v[60:61], v[20:21] op_sel:[0,1,0]
	ds_read_b128 v[120:123], v42 offset:5632
	s_waitcnt lgkmcnt(10)
	v_pk_fma_f32 v[22:23], v[90:91], v[62:63], v[22:23] op_sel_hi:[1,0,1]
	v_pk_fma_f32 v[20:21], v[88:89], v[62:63], v[20:21] op_sel_hi:[1,0,1]
	ds_read_b128 v[124:127], v42 offset:5888
	s_waitcnt lgkmcnt(10)
	v_pk_fma_f32 v[22:23], v[94:95], v[62:63], v[22:23] op_sel:[0,1,0]
	v_pk_fma_f32 v[20:21], v[92:93], v[62:63], v[20:21] op_sel:[0,1,0]
	ds_read_b128 v[56:59], v39 offset:96
	ds_read_b128 v[80:83], v42 offset:6144
	s_waitcnt lgkmcnt(10)
	v_pk_fma_f32 v[22:23], v[98:99], v[48:49], v[22:23] op_sel_hi:[1,0,1]
	v_pk_fma_f32 v[20:21], v[96:97], v[48:49], v[20:21] op_sel_hi:[1,0,1]
	ds_read_b128 v[84:87], v42 offset:6400
	s_waitcnt lgkmcnt(10)
	v_pk_fma_f32 v[22:23], v[102:103], v[48:49], v[22:23] op_sel:[0,1,0]
	v_pk_fma_f32 v[20:21], v[100:101], v[48:49], v[20:21] op_sel:[0,1,0]
	ds_read_b128 v[88:91], v42 offset:6656
	s_waitcnt lgkmcnt(10)
	v_pk_fma_f32 v[22:23], v[106:107], v[50:51], v[22:23] op_sel_hi:[1,0,1]
	v_pk_fma_f32 v[20:21], v[104:105], v[50:51], v[20:21] op_sel_hi:[1,0,1]
	ds_read_b128 v[92:95], v42 offset:6912
	s_waitcnt lgkmcnt(10)
	v_pk_fma_f32 v[22:23], v[110:111], v[50:51], v[22:23] op_sel:[0,1,0]
	v_pk_fma_f32 v[20:21], v[108:109], v[50:51], v[20:21] op_sel:[0,1,0]
	ds_read_b128 v[60:63], v39 offset:112
	ds_read_b128 v[96:99], v42 offset:7168
	s_waitcnt lgkmcnt(10)
	v_pk_fma_f32 v[22:23], v[114:115], v[52:53], v[22:23] op_sel_hi:[1,0,1]
	v_pk_fma_f32 v[20:21], v[112:113], v[52:53], v[20:21] op_sel_hi:[1,0,1]
	ds_read_b128 v[100:103], v42 offset:7424
	s_waitcnt lgkmcnt(10)
	v_pk_fma_f32 v[22:23], v[118:119], v[52:53], v[22:23] op_sel:[0,1,0]
	v_pk_fma_f32 v[20:21], v[116:117], v[52:53], v[20:21] op_sel:[0,1,0]
	ds_read_b128 v[104:107], v42 offset:7680
	s_waitcnt lgkmcnt(10)
	v_pk_fma_f32 v[22:23], v[122:123], v[54:55], v[22:23] op_sel_hi:[1,0,1]
	v_pk_fma_f32 v[20:21], v[120:121], v[54:55], v[20:21] op_sel_hi:[1,0,1]
	ds_read_b128 v[108:111], v42 offset:7936
	s_waitcnt lgkmcnt(10)
	v_pk_fma_f32 v[22:23], v[126:127], v[54:55], v[22:23] op_sel:[0,1,0]
	v_pk_fma_f32 v[20:21], v[124:125], v[54:55], v[20:21] op_sel:[0,1,0]
	ds_read_b128 v[48:51], v39 offset:128
	ds_read_b128 v[112:115], v42 offset:8192
	s_waitcnt lgkmcnt(10)
	v_pk_fma_f32 v[22:23], v[82:83], v[56:57], v[22:23] op_sel_hi:[1,0,1]
	v_pk_fma_f32 v[20:21], v[80:81], v[56:57], v[20:21] op_sel_hi:[1,0,1]
	ds_read_b128 v[116:119], v42 offset:8448
	s_waitcnt lgkmcnt(10)
	v_pk_fma_f32 v[22:23], v[86:87], v[56:57], v[22:23] op_sel:[0,1,0]
	v_pk_fma_f32 v[20:21], v[84:85], v[56:57], v[20:21] op_sel:[0,1,0]
	ds_read_b128 v[120:123], v42 offset:8704
	s_waitcnt lgkmcnt(10)
	v_pk_fma_f32 v[22:23], v[90:91], v[58:59], v[22:23] op_sel_hi:[1,0,1]
	v_pk_fma_f32 v[20:21], v[88:89], v[58:59], v[20:21] op_sel_hi:[1,0,1]
	ds_read_b128 v[124:127], v42 offset:8960
	s_waitcnt lgkmcnt(10)
	v_pk_fma_f32 v[22:23], v[94:95], v[58:59], v[22:23] op_sel:[0,1,0]
	v_pk_fma_f32 v[20:21], v[92:93], v[58:59], v[20:21] op_sel:[0,1,0]
	ds_read_b128 v[52:55], v39 offset:144
	ds_read_b128 v[80:83], v42 offset:9216
	s_waitcnt lgkmcnt(10)
	v_pk_fma_f32 v[22:23], v[98:99], v[60:61], v[22:23] op_sel_hi:[1,0,1]
	v_pk_fma_f32 v[20:21], v[96:97], v[60:61], v[20:21] op_sel_hi:[1,0,1]
	ds_read_b128 v[84:87], v42 offset:9472
	s_waitcnt lgkmcnt(10)
	v_pk_fma_f32 v[22:23], v[102:103], v[60:61], v[22:23] op_sel:[0,1,0]
	v_pk_fma_f32 v[20:21], v[100:101], v[60:61], v[20:21] op_sel:[0,1,0]
	ds_read_b128 v[88:91], v42 offset:9728
	s_waitcnt lgkmcnt(10)
	v_pk_fma_f32 v[22:23], v[106:107], v[62:63], v[22:23] op_sel_hi:[1,0,1]
	v_pk_fma_f32 v[20:21], v[104:105], v[62:63], v[20:21] op_sel_hi:[1,0,1]
	ds_read_b128 v[92:95], v42 offset:9984
	s_waitcnt lgkmcnt(10)
	v_pk_fma_f32 v[22:23], v[110:111], v[62:63], v[22:23] op_sel:[0,1,0]
	v_pk_fma_f32 v[20:21], v[108:109], v[62:63], v[20:21] op_sel:[0,1,0]
	ds_read_b128 v[56:59], v39 offset:160
	ds_read_b128 v[96:99], v42 offset:10240
	s_waitcnt lgkmcnt(10)
	v_pk_fma_f32 v[22:23], v[114:115], v[48:49], v[22:23] op_sel_hi:[1,0,1]
	v_pk_fma_f32 v[20:21], v[112:113], v[48:49], v[20:21] op_sel_hi:[1,0,1]
	ds_read_b128 v[100:103], v42 offset:10496
	s_waitcnt lgkmcnt(10)
	v_pk_fma_f32 v[22:23], v[118:119], v[48:49], v[22:23] op_sel:[0,1,0]
	v_pk_fma_f32 v[20:21], v[116:117], v[48:49], v[20:21] op_sel:[0,1,0]
	ds_read_b128 v[104:107], v42 offset:10752
	s_waitcnt lgkmcnt(10)
	v_pk_fma_f32 v[22:23], v[122:123], v[50:51], v[22:23] op_sel_hi:[1,0,1]
	v_pk_fma_f32 v[20:21], v[120:121], v[50:51], v[20:21] op_sel_hi:[1,0,1]
	ds_read_b128 v[108:111], v42 offset:11008
	s_waitcnt lgkmcnt(10)
	v_pk_fma_f32 v[22:23], v[126:127], v[50:51], v[22:23] op_sel:[0,1,0]
	v_pk_fma_f32 v[20:21], v[124:125], v[50:51], v[20:21] op_sel:[0,1,0]
	ds_read_b128 v[60:63], v39 offset:176
	ds_read_b128 v[112:115], v42 offset:11264
	s_waitcnt lgkmcnt(10)
	v_pk_fma_f32 v[22:23], v[82:83], v[52:53], v[22:23] op_sel_hi:[1,0,1]
	v_pk_fma_f32 v[20:21], v[80:81], v[52:53], v[20:21] op_sel_hi:[1,0,1]
	ds_read_b128 v[116:119], v42 offset:11520
	s_waitcnt lgkmcnt(10)
	v_pk_fma_f32 v[22:23], v[86:87], v[52:53], v[22:23] op_sel:[0,1,0]
	v_pk_fma_f32 v[20:21], v[84:85], v[52:53], v[20:21] op_sel:[0,1,0]
	ds_read_b128 v[120:123], v42 offset:11776
	s_waitcnt lgkmcnt(10)
	v_pk_fma_f32 v[22:23], v[90:91], v[54:55], v[22:23] op_sel_hi:[1,0,1]
	v_pk_fma_f32 v[20:21], v[88:89], v[54:55], v[20:21] op_sel_hi:[1,0,1]
	ds_read_b128 v[124:127], v42 offset:12032
	s_waitcnt lgkmcnt(10)
	v_pk_fma_f32 v[22:23], v[94:95], v[54:55], v[22:23] op_sel:[0,1,0]
	v_pk_fma_f32 v[20:21], v[92:93], v[54:55], v[20:21] op_sel:[0,1,0]
	ds_read_b128 v[48:51], v39 offset:192
	ds_read_b128 v[80:83], v42 offset:12288
	s_waitcnt lgkmcnt(10)
	v_pk_fma_f32 v[22:23], v[98:99], v[56:57], v[22:23] op_sel_hi:[1,0,1]
	v_pk_fma_f32 v[20:21], v[96:97], v[56:57], v[20:21] op_sel_hi:[1,0,1]
	ds_read_b128 v[84:87], v42 offset:12544
	s_waitcnt lgkmcnt(10)
	v_pk_fma_f32 v[22:23], v[102:103], v[56:57], v[22:23] op_sel:[0,1,0]
	v_pk_fma_f32 v[20:21], v[100:101], v[56:57], v[20:21] op_sel:[0,1,0]
	ds_read_b128 v[88:91], v42 offset:12800
	s_waitcnt lgkmcnt(10)
	v_pk_fma_f32 v[22:23], v[106:107], v[58:59], v[22:23] op_sel_hi:[1,0,1]
	v_pk_fma_f32 v[20:21], v[104:105], v[58:59], v[20:21] op_sel_hi:[1,0,1]
	ds_read_b128 v[92:95], v42 offset:13056
	s_waitcnt lgkmcnt(10)
	v_pk_fma_f32 v[22:23], v[110:111], v[58:59], v[22:23] op_sel:[0,1,0]
	v_pk_fma_f32 v[20:21], v[108:109], v[58:59], v[20:21] op_sel:[0,1,0]
	ds_read_b128 v[52:55], v39 offset:208
	ds_read_b128 v[96:99], v42 offset:13312
	s_waitcnt lgkmcnt(10)
	v_pk_fma_f32 v[22:23], v[114:115], v[60:61], v[22:23] op_sel_hi:[1,0,1]
	v_pk_fma_f32 v[20:21], v[112:113], v[60:61], v[20:21] op_sel_hi:[1,0,1]
	ds_read_b128 v[100:103], v42 offset:13568
	s_waitcnt lgkmcnt(10)
	v_pk_fma_f32 v[22:23], v[118:119], v[60:61], v[22:23] op_sel:[0,1,0]
	v_pk_fma_f32 v[20:21], v[116:117], v[60:61], v[20:21] op_sel:[0,1,0]
	ds_read_b128 v[104:107], v42 offset:13824
	s_waitcnt lgkmcnt(10)
	v_pk_fma_f32 v[22:23], v[122:123], v[62:63], v[22:23] op_sel_hi:[1,0,1]
	v_pk_fma_f32 v[20:21], v[120:121], v[62:63], v[20:21] op_sel_hi:[1,0,1]
	ds_read_b128 v[108:111], v42 offset:14080
	s_waitcnt lgkmcnt(10)
	v_pk_fma_f32 v[22:23], v[126:127], v[62:63], v[22:23] op_sel:[0,1,0]
	v_pk_fma_f32 v[20:21], v[124:125], v[62:63], v[20:21] op_sel:[0,1,0]
	ds_read_b128 v[56:59], v39 offset:224
	ds_read_b128 v[112:115], v42 offset:14336
	s_waitcnt lgkmcnt(10)
	v_pk_fma_f32 v[22:23], v[82:83], v[48:49], v[22:23] op_sel_hi:[1,0,1]
	v_pk_fma_f32 v[20:21], v[80:81], v[48:49], v[20:21] op_sel_hi:[1,0,1]
	ds_read_b128 v[116:119], v42 offset:14592
	s_waitcnt lgkmcnt(10)
	v_pk_fma_f32 v[22:23], v[86:87], v[48:49], v[22:23] op_sel:[0,1,0]
	v_pk_fma_f32 v[20:21], v[84:85], v[48:49], v[20:21] op_sel:[0,1,0]
	ds_read_b128 v[120:123], v42 offset:14848
	s_waitcnt lgkmcnt(10)
	v_pk_fma_f32 v[22:23], v[90:91], v[50:51], v[22:23] op_sel_hi:[1,0,1]
	v_pk_fma_f32 v[20:21], v[88:89], v[50:51], v[20:21] op_sel_hi:[1,0,1]
	ds_read_b128 v[124:127], v42 offset:15104
	s_waitcnt lgkmcnt(10)
	v_pk_fma_f32 v[22:23], v[94:95], v[50:51], v[22:23] op_sel:[0,1,0]
	v_pk_fma_f32 v[20:21], v[92:93], v[50:51], v[20:21] op_sel:[0,1,0]
	ds_read_b128 v[60:63], v39 offset:240
	ds_read_b128 v[80:83], v42 offset:15360
	s_waitcnt lgkmcnt(10)
	v_pk_fma_f32 v[22:23], v[98:99], v[52:53], v[22:23] op_sel_hi:[1,0,1]
	v_pk_fma_f32 v[20:21], v[96:97], v[52:53], v[20:21] op_sel_hi:[1,0,1]
	ds_read_b128 v[84:87], v42 offset:15616
	s_waitcnt lgkmcnt(10)
	v_pk_fma_f32 v[22:23], v[102:103], v[52:53], v[22:23] op_sel:[0,1,0]
	v_pk_fma_f32 v[20:21], v[100:101], v[52:53], v[20:21] op_sel:[0,1,0]
	ds_read_b128 v[88:91], v42 offset:15872
	s_waitcnt lgkmcnt(10)
	v_pk_fma_f32 v[22:23], v[106:107], v[54:55], v[22:23] op_sel_hi:[1,0,1]
	v_pk_fma_f32 v[20:21], v[104:105], v[54:55], v[20:21] op_sel_hi:[1,0,1]
	ds_read_b128 v[92:95], v42 offset:16128
	s_waitcnt lgkmcnt(10)
	v_pk_fma_f32 v[22:23], v[110:111], v[54:55], v[22:23] op_sel:[0,1,0]
	v_pk_fma_f32 v[20:21], v[108:109], v[54:55], v[20:21] op_sel:[0,1,0]
	s_waitcnt lgkmcnt(8)
	v_pk_fma_f32 v[22:23], v[114:115], v[56:57], v[22:23] op_sel_hi:[1,0,1]
	v_pk_fma_f32 v[20:21], v[112:113], v[56:57], v[20:21] op_sel_hi:[1,0,1]
	s_waitcnt lgkmcnt(7)
	v_pk_fma_f32 v[22:23], v[118:119], v[56:57], v[22:23] op_sel:[0,1,0]
	v_pk_fma_f32 v[20:21], v[116:117], v[56:57], v[20:21] op_sel:[0,1,0]
	s_waitcnt lgkmcnt(6)
	v_pk_fma_f32 v[22:23], v[122:123], v[58:59], v[22:23] op_sel_hi:[1,0,1]
	v_pk_fma_f32 v[20:21], v[120:121], v[58:59], v[20:21] op_sel_hi:[1,0,1]
	s_waitcnt lgkmcnt(5)
	v_pk_fma_f32 v[22:23], v[126:127], v[58:59], v[22:23] op_sel:[0,1,0]
	v_pk_fma_f32 v[20:21], v[124:125], v[58:59], v[20:21] op_sel:[0,1,0]
	s_waitcnt lgkmcnt(3)
	v_pk_fma_f32 v[22:23], v[82:83], v[60:61], v[22:23] op_sel_hi:[1,0,1]
	v_pk_fma_f32 v[20:21], v[80:81], v[60:61], v[20:21] op_sel_hi:[1,0,1]
	s_waitcnt lgkmcnt(2)
	v_pk_fma_f32 v[22:23], v[86:87], v[60:61], v[22:23] op_sel:[0,1,0]
	v_pk_fma_f32 v[20:21], v[84:85], v[60:61], v[20:21] op_sel:[0,1,0]
	s_waitcnt lgkmcnt(1)
	v_pk_fma_f32 v[22:23], v[90:91], v[62:63], v[22:23] op_sel_hi:[1,0,1]
	v_pk_fma_f32 v[20:21], v[88:89], v[62:63], v[20:21] op_sel_hi:[1,0,1]
	s_waitcnt lgkmcnt(0)
	v_pk_fma_f32 v[22:23], v[94:95], v[62:63], v[22:23] op_sel:[0,1,0]
	v_pk_fma_f32 v[20:21], v[92:93], v[62:63], v[20:21] op_sel:[0,1,0]
	v_lshl_add_u64 v[42:43], v[28:29], 2, s[4:5]
	v_lshl_add_u64 v[42:43], v[42:43], 0, v[196:197]
	s_barrier
	ds_write_b128 v40, v[20:23]
	global_store_dwordx4 v[42:43], v[20:23], off
	s_xor_b64 s[36:37], s[36:37], -1
	s_cmp_eq_u32 s23, 31
	s_waitcnt vmcnt(1)
	v_mov_b64_e32 v[22:23], v[18:19]
	v_mov_b64_e32 v[20:21], v[16:17]
	s_mov_b64 s[4:5], s[40:41]
	s_mov_b32 s42, s23
	s_cbranch_scc0 .LBB0_675
	s_mov_b64 s[0:1], 0

.LBB0_683:
	v_lshl_add_u64 v[16:17], v[6:7], 0, s[0:1]
	v_add_co_u32_e32 v20, vcc, 0xf948000, v16
	ds_read_b128 v[8:11], v25
	ds_read_b128 v[12:15], v25 offset:16
	v_addc_co_u32_e32 v21, vcc, 0, v17, vcc
	global_load_dwordx4 v[40:43], v[20:21], off
	global_load_dwordx4 v[44:47], v[20:21], off offset:256
	global_load_dwordx4 v[48:51], v[20:21], off offset:512
	global_load_dwordx4 v[52:55], v[20:21], off offset:768
	global_load_dwordx4 v[60:63], v[20:21], off offset:1024
	global_load_dwordx4 v[64:67], v[20:21], off offset:1280
	global_load_dwordx4 v[68:71], v[20:21], off offset:1536
	global_load_dwordx4 v[72:75], v[20:21], off offset:1792
	s_add_u32 s0, s0, 0x800
	s_addc_u32 s1, s1, 0
	v_add_u32_e32 v25, 32, v25
	s_waitcnt lgkmcnt(0)
	s_waitcnt vmcnt(7)
	v_pk_fma_f32 v[0:1], v[8:9], v[40:41], v[0:1] op_sel_hi:[0,1,1]
	v_pk_fma_f32 v[2:3], v[8:9], v[42:43], v[2:3] op_sel_hi:[0,1,1]
	s_waitcnt vmcnt(6)
	v_pk_fma_f32 v[0:1], v[8:9], v[44:45], v[0:1] op_sel:[1,0,0]
	v_pk_fma_f32 v[2:3], v[8:9], v[46:47], v[2:3] op_sel:[1,0,0]
	s_waitcnt vmcnt(5)
	v_pk_fma_f32 v[0:1], v[10:11], v[48:49], v[0:1] op_sel_hi:[0,1,1]
	v_pk_fma_f32 v[2:3], v[10:11], v[50:51], v[2:3] op_sel_hi:[0,1,1]
	s_waitcnt vmcnt(4)
	v_pk_fma_f32 v[0:1], v[10:11], v[52:53], v[0:1] op_sel:[1,0,0]
	v_pk_fma_f32 v[2:3], v[10:11], v[54:55], v[2:3] op_sel:[1,0,0]
	s_waitcnt vmcnt(3)
	v_pk_fma_f32 v[0:1], v[12:13], v[60:61], v[0:1] op_sel_hi:[0,1,1]
	v_pk_fma_f32 v[2:3], v[12:13], v[62:63], v[2:3] op_sel_hi:[0,1,1]
	s_waitcnt vmcnt(2)
	v_pk_fma_f32 v[0:1], v[12:13], v[64:65], v[0:1] op_sel:[1,0,0]
	v_pk_fma_f32 v[2:3], v[12:13], v[66:67], v[2:3] op_sel:[1,0,0]
	s_waitcnt vmcnt(1)
	v_pk_fma_f32 v[0:1], v[14:15], v[68:69], v[0:1] op_sel_hi:[0,1,1]
	v_pk_fma_f32 v[2:3], v[14:15], v[70:71], v[2:3] op_sel_hi:[0,1,1]
	s_waitcnt vmcnt(0)
	v_pk_fma_f32 v[0:1], v[14:15], v[72:73], v[0:1] op_sel:[1,0,0]
	v_pk_fma_f32 v[2:3], v[14:15], v[74:75], v[2:3] op_sel:[1,0,0]
	s_cmpk_eq_i32 s0, 0x4000
	s_cbranch_scc0 .LBB0_683
	s_add_i32 s3, s3, s57
	s_lshl_b32 s0, s3, 4
	s_lshl_b32 s1, s5, 3
	s_or_b32 s0, s0, s1
	s_or_b32 s0, s0, s4
	s_ashr_i32 s1, s0, 31
	s_lshl_b64 s[0:1], s[0:1], 14
	s_add_u32 s0, s54, s0
	s_addc_u32 s1, s55, s1
	v_lshl_add_u64 v[4:5], v[4:5], 2, s[0:1]
	v_lshlrev_b32_e32 v196, 2, v24
	v_lshl_add_u64 v[4:5], v[4:5], 0, v[196:197]
	global_store_dwordx4 v[4:5], v[0:3], off
	s_branch .LBB0_672
